# EpiResid bf16 path: counted vmcnt ladder (each row group waits only for its own two residual loads) instead of one vmcnt(0)
# baseline (speedup 1.0000x reference)
; DI unsigned cvtpk(float lo, float hi) { f32x2_t v = {lo, hi}; bf16x2_t b = __builtin_convertvector(v, bf16x2_t); return __builtin_bit_cast(unsigned, b); }
; DI float bflo(unsigned u) { return __uint_as_float(u << 16); }
; DI float bfhi(unsigned u) { return __uint_as_float(u & 0xffff0000u); }
;     DI void operator()(const f32x4 (&acc)[2][2][4][2], const Unit& u, int wr, int wc, int fr, int fq) const {
;     ...
;         if (baseb) {
;             u32x4 bw[2][4][2];
; #pragma unroll
;             for (int ai = 0; ai < 2; ++ai)
; #pragma unroll
;                 for (int m = 0; m < 4; ++m)
; #pragma unroll
;                     for (int bj = 0; bj < 2; ++bj) bw[ai][m][bj] = *(const u32x4*)(baseb + (size_t)(row0 + ai * HALF + m * 16) * DM + col0 + bj * HALF);
; #pragma unroll
;             for (int ai = 0; ai < 2; ++ai)
; #pragma unroll
;                 for (int m = 0; m < 4; ++m) {
;                     const int row = row0 + ai * HALF + m * 16; float ss = 0.f;
; #pragma unroll
;                     for (int bj = 0; bj < 2; ++bj) {
;                         const size_t off = (size_t)row * DM + col0 + bj * HALF; const u32x4 w = bw[ai][m][bj];
;                         const f32x4 b0 = (f32x4){bflo(w.x), bfhi(w.x), bflo(w.y), bfhi(w.y)}, b1 = (f32x4){bflo(w.z), bfhi(w.z), bflo(w.w), bfhi(w.w)};
;                         const f32x4 x0 = b0 + alpha * acc[ai][bj][m][0], x1 = b1 + alpha * acc[ai][bj][m][1];
;                         if (out) { *(f32x4*)(out + off) = x0; *(f32x4*)(out + off + 4) = x1; }
;                         if (xb) { u32x4 o; o.x = cvtpk(x0[0], x0[1]); o.y = cvtpk(x0[2], x0[3]); o.z = cvtpk(x1[0], x1[1]); o.w = cvtpk(x1[2], x1[3]); *(u32x4*)(xb + off) = o; }
;                         ss += (x0[0] * x0[0] + x0[1] * x0[1]) + (x0[2] * x0[2] + x0[3] * x0[3]) + (x1[0] * x1[0] + x1[1] * x1[1]) + (x1[2] * x1[2] + x1[3] * x1[3]);
.LBB0_456:
	v_lshl_add_u32 v234, s46, 8, v250
	v_lshl_or_b32 v220, s95, 8, v252
	v_or_b32_e32 v232, 16, v234
	v_or_b32_e32 v230, 32, v234
	v_or_b32_e32 v228, 48, v234
	v_add_u32_e32 v226, 0x80, v234
	v_add_u32_e32 v224, 0x90, v234
	v_add_u32_e32 v222, 0xa0, v234
	v_add_u32_e32 v218, 0xb0, v234
	v_cndmask_b32_e64 v130, 0, 1, s[78:79]
	v_ashrrev_i32_e32 v221, 31, v220
	s_and_b64 vcc, exec, s[58:59]
	v_ashrrev_i32_e32 v235, 31, v234
	v_ashrrev_i32_e32 v233, 31, v232
	v_ashrrev_i32_e32 v231, 31, v230
	v_ashrrev_i32_e32 v229, 31, v228
	v_ashrrev_i32_e32 v227, 31, v226
	v_ashrrev_i32_e32 v225, 31, v224
	v_ashrrev_i32_e32 v223, 31, v222
	v_ashrrev_i32_e32 v219, 31, v218
	v_cmp_ne_u32_e64 s[8:9], 1, v130
	s_cbranch_vccz .LBB0_651
	v_lshl_add_u64 v[130:131], v[220:221], 1, s[34:35]
	v_lshlrev_b64 v[132:133], 11, v[234:235]
	v_lshl_add_u64 v[132:133], v[130:131], 0, v[132:133]
	global_load_dwordx4 v[190:193], v[132:133], off
	global_load_dwordx4 v[186:189], v[132:133], off offset:256
	v_lshlrev_b64 v[132:133], 11, v[232:233]
	v_lshl_add_u64 v[132:133], v[130:131], 0, v[132:133]
	global_load_dwordx4 v[182:185], v[132:133], off
	global_load_dwordx4 v[178:181], v[132:133], off offset:256
	v_lshlrev_b64 v[132:133], 11, v[230:231]
	v_lshl_add_u64 v[132:133], v[130:131], 0, v[132:133]
	global_load_dwordx4 v[174:177], v[132:133], off
	global_load_dwordx4 v[170:173], v[132:133], off offset:256
	v_lshlrev_b64 v[132:133], 11, v[228:229]
	v_lshl_add_u64 v[132:133], v[130:131], 0, v[132:133]
	global_load_dwordx4 v[166:169], v[132:133], off
	global_load_dwordx4 v[162:165], v[132:133], off offset:256
	v_lshlrev_b64 v[132:133], 11, v[226:227]
	v_lshl_add_u64 v[132:133], v[130:131], 0, v[132:133]
	global_load_dwordx4 v[158:161], v[132:133], off
	global_load_dwordx4 v[154:157], v[132:133], off offset:256
	v_lshlrev_b64 v[132:133], 11, v[224:225]
	v_lshl_add_u64 v[132:133], v[130:131], 0, v[132:133]
	global_load_dwordx4 v[150:153], v[132:133], off
	global_load_dwordx4 v[146:149], v[132:133], off offset:256
	v_lshlrev_b64 v[132:133], 11, v[222:223]
	v_lshl_add_u64 v[132:133], v[130:131], 0, v[132:133]
	global_load_dwordx4 v[142:145], v[132:133], off
	global_load_dwordx4 v[138:141], v[132:133], off offset:256
	v_lshlrev_b64 v[132:133], 11, v[218:219]
	v_lshl_add_u64 v[130:131], v[130:131], 0, v[132:133]
	global_load_dwordx4 v[134:137], v[130:131], off
	s_nop 0
	global_load_dwordx4 v[130:133], v[130:131], off offset:256
	v_lshlrev_b64 v[194:195], 10, v[234:235]
	v_lshl_add_u64 v[198:199], v[194:195], 0, v[220:221]
	s_and_b64 vcc, exec, s[8:9]
	v_lshl_add_u64 v[238:239], v[198:199], 2, s[40:41]
	s_waitcnt vmcnt(15)
	v_lshlrev_b32_e32 v194, 16, v190
	v_and_b32_e32 v195, 0xffff0000, v190
	v_lshlrev_b32_e32 v190, 16, v191
	v_and_b32_e32 v191, 0xffff0000, v191
	v_lshlrev_b32_e32 v200, 16, v192
	v_and_b32_e32 v201, 0xffff0000, v192
	v_lshlrev_b32_e32 v192, 16, v193
	v_and_b32_e32 v193, 0xffff0000, v193
	v_pk_fma_f32 v[196:197], s[84:85], v[128:129], v[190:191]
	v_pk_fma_f32 v[194:195], s[66:67], v[126:127], v[194:195]
	v_pk_fma_f32 v[192:193], s[84:85], v[124:125], v[192:193]
	v_pk_fma_f32 v[190:191], s[66:67], v[122:123], v[200:201]
	s_cbranch_vccnz .LBB0_459
	global_store_dwordx4 v[238:239], v[194:197], off
	global_store_dwordx4 v[238:239], v[190:193], off offset:16

; DI unsigned cvtpk(float lo, float hi) { f32x2_t v = {lo, hi}; bf16x2_t b = __builtin_convertvector(v, bf16x2_t); return __builtin_bit_cast(unsigned, b); }
; DI float bflo(unsigned u) { return __uint_as_float(u << 16); }
; DI float bfhi(unsigned u) { return __uint_as_float(u & 0xffff0000u); }
;     DI void operator()(const f32x4 (&acc)[2][2][4][2], const Unit& u, int wr, int wc, int fr, int fq) const {
;     ...
;                     const int row = row0 + ai * HALF + m * 16; float ss = 0.f;
; #pragma unroll
;                     for (int bj = 0; bj < 2; ++bj) {
;                         const size_t off = (size_t)row * DM + col0 + bj * HALF; const u32x4 w = bw[ai][m][bj];
;                         const f32x4 b0 = (f32x4){bflo(w.x), bfhi(w.x), bflo(w.y), bfhi(w.y)}, b1 = (f32x4){bflo(w.z), bfhi(w.z), bflo(w.w), bfhi(w.w)};
;                         const f32x4 x0 = b0 + alpha * acc[ai][bj][m][0], x1 = b1 + alpha * acc[ai][bj][m][1];
;                         if (out) { *(f32x4*)(out + off) = x0; *(f32x4*)(out + off + 4) = x1; }
;                         if (xb) { u32x4 o; o.x = cvtpk(x0[0], x0[1]); o.y = cvtpk(x0[2], x0[3]); o.z = cvtpk(x1[0], x1[1]); o.w = cvtpk(x1[2], x1[3]); *(u32x4*)(xb + off) = o; }
;                         ss += (x0[0] * x0[0] + x0[1] * x0[1]) + (x0[2] * x0[2] + x0[3] * x0[3]) + (x1[0] * x1[0] + x1[1] * x1[1]) + (x1[2] * x1[2] + x1[3] * x1[3]);
.LBB0_461:
	s_nop 1
	s_waitcnt vmcnt(14)
	v_lshlrev_b32_e32 v198, 16, v186
	v_and_b32_e32 v199, 0xffff0000, v186
	v_lshlrev_b32_e32 v186, 16, v187
	v_and_b32_e32 v187, 0xffff0000, v187
	v_lshlrev_b32_e32 v202, 16, v188
	v_and_b32_e32 v203, 0xffff0000, v188
	v_lshlrev_b32_e32 v200, 16, v189
	v_and_b32_e32 v201, 0xffff0000, v189
	v_pk_fma_f32 v[188:189], s[84:85], v[120:121], v[186:187]
	v_pk_fma_f32 v[186:187], s[66:67], v[118:119], v[198:199]
	v_pk_fma_f32 v[200:201], s[84:85], v[116:117], v[200:201]
	s_and_b64 vcc, exec, s[8:9]
	v_pk_fma_f32 v[198:199], s[66:67], v[114:115], v[202:203]
	s_cbranch_vccnz .LBB0_463
	global_store_dwordx4 v[238:239], v[186:189], off offset:512
	global_store_dwordx4 v[238:239], v[198:201], off offset:528

; DI unsigned cvtpk(float lo, float hi) { f32x2_t v = {lo, hi}; bf16x2_t b = __builtin_convertvector(v, bf16x2_t); return __builtin_bit_cast(unsigned, b); }
; DI float bflo(unsigned u) { return __uint_as_float(u << 16); }
; DI float bfhi(unsigned u) { return __uint_as_float(u & 0xffff0000u); }
;     DI void operator()(const f32x4 (&acc)[2][2][4][2], const Unit& u, int wr, int wc, int fr, int fq) const {
;     ...
;                     const int row = row0 + ai * HALF + m * 16; float ss = 0.f;
; #pragma unroll
;                     for (int bj = 0; bj < 2; ++bj) {
;                         const size_t off = (size_t)row * DM + col0 + bj * HALF; const u32x4 w = bw[ai][m][bj];
;                         const f32x4 b0 = (f32x4){bflo(w.x), bfhi(w.x), bflo(w.y), bfhi(w.y)}, b1 = (f32x4){bflo(w.z), bfhi(w.z), bflo(w.w), bfhi(w.w)};
;                         const f32x4 x0 = b0 + alpha * acc[ai][bj][m][0], x1 = b1 + alpha * acc[ai][bj][m][1];
;                         if (out) { *(f32x4*)(out + off) = x0; *(f32x4*)(out + off + 4) = x1; }
;                         if (xb) { u32x4 o; o.x = cvtpk(x0[0], x0[1]); o.y = cvtpk(x0[2], x0[3]); o.z = cvtpk(x1[0], x1[1]); o.w = cvtpk(x1[2], x1[3]); *(u32x4*)(xb + off) = o; }
;                         ss += (x0[0] * x0[0] + x0[1] * x0[1]) + (x0[2] * x0[2] + x0[3] * x0[3]) + (x1[0] * x1[0] + x1[1] * x1[1]) + (x1[2] * x1[2] + x1[3] * x1[3]);
.LBB0_469:
	s_waitcnt lgkmcnt(0)
	v_lshlrev_b64 v[186:187], 10, v[232:233]
	v_lshl_add_u64 v[190:191], v[186:187], 0, v[220:221]
	s_waitcnt vmcnt(13)
	v_lshlrev_b32_e32 v186, 16, v182
	v_and_b32_e32 v187, 0xffff0000, v182
	v_lshlrev_b32_e32 v182, 16, v183
	v_and_b32_e32 v183, 0xffff0000, v183
	v_lshlrev_b32_e32 v192, 16, v184
	v_and_b32_e32 v193, 0xffff0000, v184
	v_lshlrev_b32_e32 v188, 16, v185
	v_and_b32_e32 v189, 0xffff0000, v185
	v_pk_fma_f32 v[184:185], s[84:85], v[112:113], v[182:183]
	v_pk_fma_f32 v[182:183], s[66:67], v[110:111], v[186:187]
	v_pk_fma_f32 v[188:189], s[84:85], v[108:109], v[188:189]
	v_pk_fma_f32 v[186:187], s[66:67], v[106:107], v[192:193]
	s_and_b64 vcc, exec, s[8:9]
	v_lshl_add_u64 v[196:197], v[190:191], 2, s[40:41]
	s_cbranch_vccnz .LBB0_471
	global_store_dwordx4 v[196:197], v[182:185], off
	global_store_dwordx4 v[196:197], v[186:189], off offset:16

; DI unsigned cvtpk(float lo, float hi) { f32x2_t v = {lo, hi}; bf16x2_t b = __builtin_convertvector(v, bf16x2_t); return __builtin_bit_cast(unsigned, b); }
; DI float bflo(unsigned u) { return __uint_as_float(u << 16); }
; DI float bfhi(unsigned u) { return __uint_as_float(u & 0xffff0000u); }
;     DI void operator()(const f32x4 (&acc)[2][2][4][2], const Unit& u, int wr, int wc, int fr, int fq) const {
;     ...
;                     const int row = row0 + ai * HALF + m * 16; float ss = 0.f;
; #pragma unroll
;                     for (int bj = 0; bj < 2; ++bj) {
;                         const size_t off = (size_t)row * DM + col0 + bj * HALF; const u32x4 w = bw[ai][m][bj];
;                         const f32x4 b0 = (f32x4){bflo(w.x), bfhi(w.x), bflo(w.y), bfhi(w.y)}, b1 = (f32x4){bflo(w.z), bfhi(w.z), bflo(w.w), bfhi(w.w)};
;                         const f32x4 x0 = b0 + alpha * acc[ai][bj][m][0], x1 = b1 + alpha * acc[ai][bj][m][1];
;                         if (out) { *(f32x4*)(out + off) = x0; *(f32x4*)(out + off + 4) = x1; }
;                         if (xb) { u32x4 o; o.x = cvtpk(x0[0], x0[1]); o.y = cvtpk(x0[2], x0[3]); o.z = cvtpk(x1[0], x1[1]); o.w = cvtpk(x1[2], x1[3]); *(u32x4*)(xb + off) = o; }
;                         ss += (x0[0] * x0[0] + x0[1] * x0[1]) + (x0[2] * x0[2] + x0[3] * x0[3]) + (x1[0] * x1[0] + x1[1] * x1[1]) + (x1[2] * x1[2] + x1[3] * x1[3]);
.LBB0_473:
	s_nop 1
	s_waitcnt vmcnt(12)
	v_lshlrev_b32_e32 v190, 16, v178
	v_and_b32_e32 v191, 0xffff0000, v178
	v_lshlrev_b32_e32 v178, 16, v179
	v_and_b32_e32 v179, 0xffff0000, v179
	v_lshlrev_b32_e32 v198, 16, v180
	v_and_b32_e32 v199, 0xffff0000, v180
	v_lshlrev_b32_e32 v192, 16, v181
	v_and_b32_e32 v193, 0xffff0000, v181
	v_pk_fma_f32 v[180:181], s[84:85], v[104:105], v[178:179]
	v_pk_fma_f32 v[178:179], s[66:67], v[102:103], v[190:191]
	v_pk_fma_f32 v[192:193], s[84:85], v[100:101], v[192:193]
	s_and_b64 vcc, exec, s[8:9]
	v_pk_fma_f32 v[190:191], s[66:67], v[98:99], v[198:199]
	s_cbranch_vccnz .LBB0_475
	global_store_dwordx4 v[196:197], v[178:181], off offset:512
	global_store_dwordx4 v[196:197], v[190:193], off offset:528

; DI unsigned cvtpk(float lo, float hi) { f32x2_t v = {lo, hi}; bf16x2_t b = __builtin_convertvector(v, bf16x2_t); return __builtin_bit_cast(unsigned, b); }
; DI float bflo(unsigned u) { return __uint_as_float(u << 16); }
; DI float bfhi(unsigned u) { return __uint_as_float(u & 0xffff0000u); }
;     DI void operator()(const f32x4 (&acc)[2][2][4][2], const Unit& u, int wr, int wc, int fr, int fq) const {
;     ...
;                     const int row = row0 + ai * HALF + m * 16; float ss = 0.f;
; #pragma unroll
;                     for (int bj = 0; bj < 2; ++bj) {
;                         const size_t off = (size_t)row * DM + col0 + bj * HALF; const u32x4 w = bw[ai][m][bj];
;                         const f32x4 b0 = (f32x4){bflo(w.x), bfhi(w.x), bflo(w.y), bfhi(w.y)}, b1 = (f32x4){bflo(w.z), bfhi(w.z), bflo(w.w), bfhi(w.w)};
;                         const f32x4 x0 = b0 + alpha * acc[ai][bj][m][0], x1 = b1 + alpha * acc[ai][bj][m][1];
;                         if (out) { *(f32x4*)(out + off) = x0; *(f32x4*)(out + off + 4) = x1; }
;                         if (xb) { u32x4 o; o.x = cvtpk(x0[0], x0[1]); o.y = cvtpk(x0[2], x0[3]); o.z = cvtpk(x1[0], x1[1]); o.w = cvtpk(x1[2], x1[3]); *(u32x4*)(xb + off) = o; }
;                         ss += (x0[0] * x0[0] + x0[1] * x0[1]) + (x0[2] * x0[2] + x0[3] * x0[3]) + (x1[0] * x1[0] + x1[1] * x1[1]) + (x1[2] * x1[2] + x1[3] * x1[3]);
.LBB0_481:
	s_waitcnt lgkmcnt(0)
	v_lshlrev_b64 v[178:179], 10, v[230:231]
	v_lshl_add_u64 v[182:183], v[178:179], 0, v[220:221]
	s_waitcnt vmcnt(11)
	v_lshlrev_b32_e32 v178, 16, v174
	v_and_b32_e32 v179, 0xffff0000, v174
	v_lshlrev_b32_e32 v174, 16, v175
	v_and_b32_e32 v175, 0xffff0000, v175
	v_lshlrev_b32_e32 v184, 16, v176
	v_and_b32_e32 v185, 0xffff0000, v176
	v_lshlrev_b32_e32 v180, 16, v177
	v_and_b32_e32 v181, 0xffff0000, v177
	v_pk_fma_f32 v[176:177], s[84:85], v[96:97], v[174:175]
	v_pk_fma_f32 v[174:175], s[66:67], v[94:95], v[178:179]
	v_pk_fma_f32 v[180:181], s[84:85], v[92:93], v[180:181]
	v_pk_fma_f32 v[178:179], s[66:67], v[90:91], v[184:185]
	s_and_b64 vcc, exec, s[8:9]
	v_lshl_add_u64 v[188:189], v[182:183], 2, s[40:41]
	s_cbranch_vccnz .LBB0_483
	global_store_dwordx4 v[188:189], v[174:177], off
	global_store_dwordx4 v[188:189], v[178:181], off offset:16

; DI unsigned cvtpk(float lo, float hi) { f32x2_t v = {lo, hi}; bf16x2_t b = __builtin_convertvector(v, bf16x2_t); return __builtin_bit_cast(unsigned, b); }
; DI float bflo(unsigned u) { return __uint_as_float(u << 16); }
; DI float bfhi(unsigned u) { return __uint_as_float(u & 0xffff0000u); }
;     DI void operator()(const f32x4 (&acc)[2][2][4][2], const Unit& u, int wr, int wc, int fr, int fq) const {
;     ...
;                     const int row = row0 + ai * HALF + m * 16; float ss = 0.f;
; #pragma unroll
;                     for (int bj = 0; bj < 2; ++bj) {
;                         const size_t off = (size_t)row * DM + col0 + bj * HALF; const u32x4 w = bw[ai][m][bj];
;                         const f32x4 b0 = (f32x4){bflo(w.x), bfhi(w.x), bflo(w.y), bfhi(w.y)}, b1 = (f32x4){bflo(w.z), bfhi(w.z), bflo(w.w), bfhi(w.w)};
;                         const f32x4 x0 = b0 + alpha * acc[ai][bj][m][0], x1 = b1 + alpha * acc[ai][bj][m][1];
;                         if (out) { *(f32x4*)(out + off) = x0; *(f32x4*)(out + off + 4) = x1; }
;                         if (xb) { u32x4 o; o.x = cvtpk(x0[0], x0[1]); o.y = cvtpk(x0[2], x0[3]); o.z = cvtpk(x1[0], x1[1]); o.w = cvtpk(x1[2], x1[3]); *(u32x4*)(xb + off) = o; }
;                         ss += (x0[0] * x0[0] + x0[1] * x0[1]) + (x0[2] * x0[2] + x0[3] * x0[3]) + (x1[0] * x1[0] + x1[1] * x1[1]) + (x1[2] * x1[2] + x1[3] * x1[3]);
.LBB0_485:
	s_nop 1
	s_waitcnt vmcnt(10)
	v_lshlrev_b32_e32 v182, 16, v170
	v_and_b32_e32 v183, 0xffff0000, v170
	v_lshlrev_b32_e32 v170, 16, v171
	v_and_b32_e32 v171, 0xffff0000, v171
	v_lshlrev_b32_e32 v190, 16, v172
	v_and_b32_e32 v191, 0xffff0000, v172
	v_lshlrev_b32_e32 v184, 16, v173
	v_and_b32_e32 v185, 0xffff0000, v173
	v_pk_fma_f32 v[172:173], s[84:85], v[88:89], v[170:171]
	v_pk_fma_f32 v[170:171], s[66:67], v[86:87], v[182:183]
	v_pk_fma_f32 v[184:185], s[84:85], v[84:85], v[184:185]
	s_and_b64 vcc, exec, s[8:9]
	v_pk_fma_f32 v[182:183], s[66:67], v[82:83], v[190:191]
	s_cbranch_vccnz .LBB0_487
	global_store_dwordx4 v[188:189], v[170:173], off offset:512
	global_store_dwordx4 v[188:189], v[182:185], off offset:528

; DI unsigned cvtpk(float lo, float hi) { f32x2_t v = {lo, hi}; bf16x2_t b = __builtin_convertvector(v, bf16x2_t); return __builtin_bit_cast(unsigned, b); }
; DI float bflo(unsigned u) { return __uint_as_float(u << 16); }
; DI float bfhi(unsigned u) { return __uint_as_float(u & 0xffff0000u); }
;     DI void operator()(const f32x4 (&acc)[2][2][4][2], const Unit& u, int wr, int wc, int fr, int fq) const {
;     ...
;                     const int row = row0 + ai * HALF + m * 16; float ss = 0.f;
; #pragma unroll
;                     for (int bj = 0; bj < 2; ++bj) {
;                         const size_t off = (size_t)row * DM + col0 + bj * HALF; const u32x4 w = bw[ai][m][bj];
;                         const f32x4 b0 = (f32x4){bflo(w.x), bfhi(w.x), bflo(w.y), bfhi(w.y)}, b1 = (f32x4){bflo(w.z), bfhi(w.z), bflo(w.w), bfhi(w.w)};
;                         const f32x4 x0 = b0 + alpha * acc[ai][bj][m][0], x1 = b1 + alpha * acc[ai][bj][m][1];
;                         if (out) { *(f32x4*)(out + off) = x0; *(f32x4*)(out + off + 4) = x1; }
;                         if (xb) { u32x4 o; o.x = cvtpk(x0[0], x0[1]); o.y = cvtpk(x0[2], x0[3]); o.z = cvtpk(x1[0], x1[1]); o.w = cvtpk(x1[2], x1[3]); *(u32x4*)(xb + off) = o; }
;                         ss += (x0[0] * x0[0] + x0[1] * x0[1]) + (x0[2] * x0[2] + x0[3] * x0[3]) + (x1[0] * x1[0] + x1[1] * x1[1]) + (x1[2] * x1[2] + x1[3] * x1[3]);
.LBB0_493:
	s_waitcnt lgkmcnt(0)
	v_lshlrev_b64 v[170:171], 10, v[228:229]
	v_lshl_add_u64 v[174:175], v[170:171], 0, v[220:221]
	s_waitcnt vmcnt(9)
	v_lshlrev_b32_e32 v170, 16, v166
	v_and_b32_e32 v171, 0xffff0000, v166
	v_lshlrev_b32_e32 v166, 16, v167
	v_and_b32_e32 v167, 0xffff0000, v167
	v_lshlrev_b32_e32 v176, 16, v168
	v_and_b32_e32 v177, 0xffff0000, v168
	v_lshlrev_b32_e32 v172, 16, v169
	v_and_b32_e32 v173, 0xffff0000, v169
	v_pk_fma_f32 v[168:169], s[84:85], v[80:81], v[166:167]
	v_pk_fma_f32 v[166:167], s[66:67], v[78:79], v[170:171]
	v_pk_fma_f32 v[172:173], s[84:85], v[76:77], v[172:173]
	v_pk_fma_f32 v[170:171], s[66:67], v[74:75], v[176:177]
	s_and_b64 vcc, exec, s[8:9]
	v_lshl_add_u64 v[180:181], v[174:175], 2, s[40:41]
	s_cbranch_vccnz .LBB0_495
	global_store_dwordx4 v[180:181], v[166:169], off
	global_store_dwordx4 v[180:181], v[170:173], off offset:16

; DI unsigned cvtpk(float lo, float hi) { f32x2_t v = {lo, hi}; bf16x2_t b = __builtin_convertvector(v, bf16x2_t); return __builtin_bit_cast(unsigned, b); }
; DI float bflo(unsigned u) { return __uint_as_float(u << 16); }
; DI float bfhi(unsigned u) { return __uint_as_float(u & 0xffff0000u); }
;     DI void operator()(const f32x4 (&acc)[2][2][4][2], const Unit& u, int wr, int wc, int fr, int fq) const {
;     ...
;                     const int row = row0 + ai * HALF + m * 16; float ss = 0.f;
; #pragma unroll
;                     for (int bj = 0; bj < 2; ++bj) {
;                         const size_t off = (size_t)row * DM + col0 + bj * HALF; const u32x4 w = bw[ai][m][bj];
;                         const f32x4 b0 = (f32x4){bflo(w.x), bfhi(w.x), bflo(w.y), bfhi(w.y)}, b1 = (f32x4){bflo(w.z), bfhi(w.z), bflo(w.w), bfhi(w.w)};
;                         const f32x4 x0 = b0 + alpha * acc[ai][bj][m][0], x1 = b1 + alpha * acc[ai][bj][m][1];
;                         if (out) { *(f32x4*)(out + off) = x0; *(f32x4*)(out + off + 4) = x1; }
;                         if (xb) { u32x4 o; o.x = cvtpk(x0[0], x0[1]); o.y = cvtpk(x0[2], x0[3]); o.z = cvtpk(x1[0], x1[1]); o.w = cvtpk(x1[2], x1[3]); *(u32x4*)(xb + off) = o; }
;                         ss += (x0[0] * x0[0] + x0[1] * x0[1]) + (x0[2] * x0[2] + x0[3] * x0[3]) + (x1[0] * x1[0] + x1[1] * x1[1]) + (x1[2] * x1[2] + x1[3] * x1[3]);
.LBB0_497:
	s_nop 1
	s_waitcnt vmcnt(8)
	v_lshlrev_b32_e32 v174, 16, v162
	v_and_b32_e32 v175, 0xffff0000, v162
	v_lshlrev_b32_e32 v162, 16, v163
	v_and_b32_e32 v163, 0xffff0000, v163
	v_lshlrev_b32_e32 v182, 16, v164
	v_and_b32_e32 v183, 0xffff0000, v164
	v_lshlrev_b32_e32 v176, 16, v165
	v_and_b32_e32 v177, 0xffff0000, v165
	v_pk_fma_f32 v[164:165], s[84:85], v[72:73], v[162:163]
	v_pk_fma_f32 v[162:163], s[66:67], v[70:71], v[174:175]
	v_pk_fma_f32 v[176:177], s[84:85], v[68:69], v[176:177]
	s_and_b64 vcc, exec, s[8:9]
	v_pk_fma_f32 v[174:175], s[66:67], v[66:67], v[182:183]
	s_cbranch_vccnz .LBB0_499
	global_store_dwordx4 v[180:181], v[162:165], off offset:512
	global_store_dwordx4 v[180:181], v[174:177], off offset:528

; DI unsigned cvtpk(float lo, float hi) { f32x2_t v = {lo, hi}; bf16x2_t b = __builtin_convertvector(v, bf16x2_t); return __builtin_bit_cast(unsigned, b); }
; DI float bflo(unsigned u) { return __uint_as_float(u << 16); }
; DI float bfhi(unsigned u) { return __uint_as_float(u & 0xffff0000u); }
;     DI void operator()(const f32x4 (&acc)[2][2][4][2], const Unit& u, int wr, int wc, int fr, int fq) const {
;     ...
;                     const int row = row0 + ai * HALF + m * 16; float ss = 0.f;
; #pragma unroll
;                     for (int bj = 0; bj < 2; ++bj) {
;                         const size_t off = (size_t)row * DM + col0 + bj * HALF; const u32x4 w = bw[ai][m][bj];
;                         const f32x4 b0 = (f32x4){bflo(w.x), bfhi(w.x), bflo(w.y), bfhi(w.y)}, b1 = (f32x4){bflo(w.z), bfhi(w.z), bflo(w.w), bfhi(w.w)};
;                         const f32x4 x0 = b0 + alpha * acc[ai][bj][m][0], x1 = b1 + alpha * acc[ai][bj][m][1];
;                         if (out) { *(f32x4*)(out + off) = x0; *(f32x4*)(out + off + 4) = x1; }
;                         if (xb) { u32x4 o; o.x = cvtpk(x0[0], x0[1]); o.y = cvtpk(x0[2], x0[3]); o.z = cvtpk(x1[0], x1[1]); o.w = cvtpk(x1[2], x1[3]); *(u32x4*)(xb + off) = o; }
;                         ss += (x0[0] * x0[0] + x0[1] * x0[1]) + (x0[2] * x0[2] + x0[3] * x0[3]) + (x1[0] * x1[0] + x1[1] * x1[1]) + (x1[2] * x1[2] + x1[3] * x1[3]);
.LBB0_505:
	s_waitcnt lgkmcnt(0)
	v_lshlrev_b64 v[162:163], 10, v[226:227]
	v_lshl_add_u64 v[166:167], v[162:163], 0, v[220:221]
	s_waitcnt vmcnt(7)
	v_lshlrev_b32_e32 v162, 16, v158
	v_and_b32_e32 v163, 0xffff0000, v158
	v_lshlrev_b32_e32 v158, 16, v159
	v_and_b32_e32 v159, 0xffff0000, v159
	v_lshlrev_b32_e32 v168, 16, v160
	v_and_b32_e32 v169, 0xffff0000, v160
	v_lshlrev_b32_e32 v164, 16, v161
	v_and_b32_e32 v165, 0xffff0000, v161
	v_pk_fma_f32 v[160:161], s[84:85], v[64:65], v[158:159]
	v_pk_fma_f32 v[158:159], s[66:67], v[62:63], v[162:163]
	v_pk_fma_f32 v[164:165], s[84:85], v[60:61], v[164:165]
	v_pk_fma_f32 v[162:163], s[66:67], v[58:59], v[168:169]
	s_and_b64 vcc, exec, s[8:9]
	v_lshl_add_u64 v[172:173], v[166:167], 2, s[40:41]
	s_cbranch_vccnz .LBB0_507
	global_store_dwordx4 v[172:173], v[158:161], off
	global_store_dwordx4 v[172:173], v[162:165], off offset:16

; DI unsigned cvtpk(float lo, float hi) { f32x2_t v = {lo, hi}; bf16x2_t b = __builtin_convertvector(v, bf16x2_t); return __builtin_bit_cast(unsigned, b); }
; DI float bflo(unsigned u) { return __uint_as_float(u << 16); }
; DI float bfhi(unsigned u) { return __uint_as_float(u & 0xffff0000u); }
;     DI void operator()(const f32x4 (&acc)[2][2][4][2], const Unit& u, int wr, int wc, int fr, int fq) const {
;     ...
;                     const int row = row0 + ai * HALF + m * 16; float ss = 0.f;
; #pragma unroll
;                     for (int bj = 0; bj < 2; ++bj) {
;                         const size_t off = (size_t)row * DM + col0 + bj * HALF; const u32x4 w = bw[ai][m][bj];
;                         const f32x4 b0 = (f32x4){bflo(w.x), bfhi(w.x), bflo(w.y), bfhi(w.y)}, b1 = (f32x4){bflo(w.z), bfhi(w.z), bflo(w.w), bfhi(w.w)};
;                         const f32x4 x0 = b0 + alpha * acc[ai][bj][m][0], x1 = b1 + alpha * acc[ai][bj][m][1];
;                         if (out) { *(f32x4*)(out + off) = x0; *(f32x4*)(out + off + 4) = x1; }
;                         if (xb) { u32x4 o; o.x = cvtpk(x0[0], x0[1]); o.y = cvtpk(x0[2], x0[3]); o.z = cvtpk(x1[0], x1[1]); o.w = cvtpk(x1[2], x1[3]); *(u32x4*)(xb + off) = o; }
;                         ss += (x0[0] * x0[0] + x0[1] * x0[1]) + (x0[2] * x0[2] + x0[3] * x0[3]) + (x1[0] * x1[0] + x1[1] * x1[1]) + (x1[2] * x1[2] + x1[3] * x1[3]);
.LBB0_509:
	s_nop 1
	s_waitcnt vmcnt(6)
	v_lshlrev_b32_e32 v166, 16, v154
	v_and_b32_e32 v167, 0xffff0000, v154
	v_lshlrev_b32_e32 v154, 16, v155
	v_and_b32_e32 v155, 0xffff0000, v155
	v_lshlrev_b32_e32 v174, 16, v156
	v_and_b32_e32 v175, 0xffff0000, v156
	v_lshlrev_b32_e32 v168, 16, v157
	v_and_b32_e32 v169, 0xffff0000, v157
	v_pk_fma_f32 v[156:157], s[84:85], v[56:57], v[154:155]
	v_pk_fma_f32 v[154:155], s[66:67], v[54:55], v[166:167]
	v_pk_fma_f32 v[168:169], s[84:85], v[52:53], v[168:169]
	s_and_b64 vcc, exec, s[8:9]
	v_pk_fma_f32 v[166:167], s[66:67], v[50:51], v[174:175]
	s_cbranch_vccnz .LBB0_511
	global_store_dwordx4 v[172:173], v[154:157], off offset:512
	global_store_dwordx4 v[172:173], v[166:169], off offset:528

; DI unsigned cvtpk(float lo, float hi) { f32x2_t v = {lo, hi}; bf16x2_t b = __builtin_convertvector(v, bf16x2_t); return __builtin_bit_cast(unsigned, b); }
; DI float bflo(unsigned u) { return __uint_as_float(u << 16); }
; DI float bfhi(unsigned u) { return __uint_as_float(u & 0xffff0000u); }
;     DI void operator()(const f32x4 (&acc)[2][2][4][2], const Unit& u, int wr, int wc, int fr, int fq) const {
;     ...
;                     const int row = row0 + ai * HALF + m * 16; float ss = 0.f;
; #pragma unroll
;                     for (int bj = 0; bj < 2; ++bj) {
;                         const size_t off = (size_t)row * DM + col0 + bj * HALF; const u32x4 w = bw[ai][m][bj];
;                         const f32x4 b0 = (f32x4){bflo(w.x), bfhi(w.x), bflo(w.y), bfhi(w.y)}, b1 = (f32x4){bflo(w.z), bfhi(w.z), bflo(w.w), bfhi(w.w)};
;                         const f32x4 x0 = b0 + alpha * acc[ai][bj][m][0], x1 = b1 + alpha * acc[ai][bj][m][1];
;                         if (out) { *(f32x4*)(out + off) = x0; *(f32x4*)(out + off + 4) = x1; }
;                         if (xb) { u32x4 o; o.x = cvtpk(x0[0], x0[1]); o.y = cvtpk(x0[2], x0[3]); o.z = cvtpk(x1[0], x1[1]); o.w = cvtpk(x1[2], x1[3]); *(u32x4*)(xb + off) = o; }
;                         ss += (x0[0] * x0[0] + x0[1] * x0[1]) + (x0[2] * x0[2] + x0[3] * x0[3]) + (x1[0] * x1[0] + x1[1] * x1[1]) + (x1[2] * x1[2] + x1[3] * x1[3]);
.LBB0_517:
	s_waitcnt lgkmcnt(0)
	v_lshlrev_b64 v[154:155], 10, v[224:225]
	v_lshl_add_u64 v[158:159], v[154:155], 0, v[220:221]
	s_waitcnt vmcnt(5)
	v_lshlrev_b32_e32 v154, 16, v150
	v_and_b32_e32 v155, 0xffff0000, v150
	v_lshlrev_b32_e32 v150, 16, v151
	v_and_b32_e32 v151, 0xffff0000, v151
	v_lshlrev_b32_e32 v160, 16, v152
	v_and_b32_e32 v161, 0xffff0000, v152
	v_lshlrev_b32_e32 v156, 16, v153
	v_and_b32_e32 v157, 0xffff0000, v153
	v_pk_fma_f32 v[152:153], s[84:85], v[48:49], v[150:151]
	v_pk_fma_f32 v[150:151], s[66:67], v[46:47], v[154:155]
	v_pk_fma_f32 v[156:157], s[84:85], v[44:45], v[156:157]
	v_pk_fma_f32 v[154:155], s[66:67], v[42:43], v[160:161]
	s_and_b64 vcc, exec, s[8:9]
	v_lshl_add_u64 v[164:165], v[158:159], 2, s[40:41]
	s_cbranch_vccnz .LBB0_519
	global_store_dwordx4 v[164:165], v[150:153], off
	global_store_dwordx4 v[164:165], v[154:157], off offset:16

; DI unsigned cvtpk(float lo, float hi) { f32x2_t v = {lo, hi}; bf16x2_t b = __builtin_convertvector(v, bf16x2_t); return __builtin_bit_cast(unsigned, b); }
; DI float bflo(unsigned u) { return __uint_as_float(u << 16); }
; DI float bfhi(unsigned u) { return __uint_as_float(u & 0xffff0000u); }
;     DI void operator()(const f32x4 (&acc)[2][2][4][2], const Unit& u, int wr, int wc, int fr, int fq) const {
;     ...
;                     const int row = row0 + ai * HALF + m * 16; float ss = 0.f;
; #pragma unroll
;                     for (int bj = 0; bj < 2; ++bj) {
;                         const size_t off = (size_t)row * DM + col0 + bj * HALF; const u32x4 w = bw[ai][m][bj];
;                         const f32x4 b0 = (f32x4){bflo(w.x), bfhi(w.x), bflo(w.y), bfhi(w.y)}, b1 = (f32x4){bflo(w.z), bfhi(w.z), bflo(w.w), bfhi(w.w)};
;                         const f32x4 x0 = b0 + alpha * acc[ai][bj][m][0], x1 = b1 + alpha * acc[ai][bj][m][1];
;                         if (out) { *(f32x4*)(out + off) = x0; *(f32x4*)(out + off + 4) = x1; }
;                         if (xb) { u32x4 o; o.x = cvtpk(x0[0], x0[1]); o.y = cvtpk(x0[2], x0[3]); o.z = cvtpk(x1[0], x1[1]); o.w = cvtpk(x1[2], x1[3]); *(u32x4*)(xb + off) = o; }
;                         ss += (x0[0] * x0[0] + x0[1] * x0[1]) + (x0[2] * x0[2] + x0[3] * x0[3]) + (x1[0] * x1[0] + x1[1] * x1[1]) + (x1[2] * x1[2] + x1[3] * x1[3]);
.LBB0_521:
	s_nop 1
	s_waitcnt vmcnt(4)
	v_lshlrev_b32_e32 v158, 16, v146
	v_and_b32_e32 v159, 0xffff0000, v146
	v_lshlrev_b32_e32 v146, 16, v147
	v_and_b32_e32 v147, 0xffff0000, v147
	v_lshlrev_b32_e32 v166, 16, v148
	v_and_b32_e32 v167, 0xffff0000, v148
	v_lshlrev_b32_e32 v160, 16, v149
	v_and_b32_e32 v161, 0xffff0000, v149
	v_pk_fma_f32 v[148:149], s[84:85], v[40:41], v[146:147]
	v_pk_fma_f32 v[146:147], s[66:67], v[38:39], v[158:159]
	v_pk_fma_f32 v[160:161], s[84:85], v[36:37], v[160:161]
	s_and_b64 vcc, exec, s[8:9]
	v_pk_fma_f32 v[158:159], s[66:67], v[34:35], v[166:167]
	s_cbranch_vccnz .LBB0_523
	global_store_dwordx4 v[164:165], v[146:149], off offset:512
	global_store_dwordx4 v[164:165], v[158:161], off offset:528

; DI unsigned cvtpk(float lo, float hi) { f32x2_t v = {lo, hi}; bf16x2_t b = __builtin_convertvector(v, bf16x2_t); return __builtin_bit_cast(unsigned, b); }
; DI float bflo(unsigned u) { return __uint_as_float(u << 16); }
; DI float bfhi(unsigned u) { return __uint_as_float(u & 0xffff0000u); }
;     DI void operator()(const f32x4 (&acc)[2][2][4][2], const Unit& u, int wr, int wc, int fr, int fq) const {
;     ...
;                     const int row = row0 + ai * HALF + m * 16; float ss = 0.f;
; #pragma unroll
;                     for (int bj = 0; bj < 2; ++bj) {
;                         const size_t off = (size_t)row * DM + col0 + bj * HALF; const u32x4 w = bw[ai][m][bj];
;                         const f32x4 b0 = (f32x4){bflo(w.x), bfhi(w.x), bflo(w.y), bfhi(w.y)}, b1 = (f32x4){bflo(w.z), bfhi(w.z), bflo(w.w), bfhi(w.w)};
;                         const f32x4 x0 = b0 + alpha * acc[ai][bj][m][0], x1 = b1 + alpha * acc[ai][bj][m][1];
;                         if (out) { *(f32x4*)(out + off) = x0; *(f32x4*)(out + off + 4) = x1; }
;                         if (xb) { u32x4 o; o.x = cvtpk(x0[0], x0[1]); o.y = cvtpk(x0[2], x0[3]); o.z = cvtpk(x1[0], x1[1]); o.w = cvtpk(x1[2], x1[3]); *(u32x4*)(xb + off) = o; }
;                         ss += (x0[0] * x0[0] + x0[1] * x0[1]) + (x0[2] * x0[2] + x0[3] * x0[3]) + (x1[0] * x1[0] + x1[1] * x1[1]) + (x1[2] * x1[2] + x1[3] * x1[3]);
.LBB0_529:
	s_waitcnt lgkmcnt(0)
	v_lshlrev_b64 v[146:147], 10, v[222:223]
	v_lshl_add_u64 v[150:151], v[146:147], 0, v[220:221]
	s_waitcnt vmcnt(3)
	v_lshlrev_b32_e32 v146, 16, v142
	v_and_b32_e32 v147, 0xffff0000, v142
	v_lshlrev_b32_e32 v142, 16, v143
	v_and_b32_e32 v143, 0xffff0000, v143
	v_lshlrev_b32_e32 v152, 16, v144
	v_and_b32_e32 v153, 0xffff0000, v144
	v_lshlrev_b32_e32 v148, 16, v145
	v_and_b32_e32 v149, 0xffff0000, v145
	v_pk_fma_f32 v[144:145], s[84:85], v[32:33], v[142:143]
	v_pk_fma_f32 v[142:143], s[66:67], v[30:31], v[146:147]
	v_pk_fma_f32 v[148:149], s[84:85], v[28:29], v[148:149]
	v_pk_fma_f32 v[146:147], s[66:67], v[26:27], v[152:153]
	s_and_b64 vcc, exec, s[8:9]
	v_lshl_add_u64 v[156:157], v[150:151], 2, s[40:41]
	s_cbranch_vccnz .LBB0_531
	global_store_dwordx4 v[156:157], v[142:145], off
	global_store_dwordx4 v[156:157], v[146:149], off offset:16

; DI unsigned cvtpk(float lo, float hi) { f32x2_t v = {lo, hi}; bf16x2_t b = __builtin_convertvector(v, bf16x2_t); return __builtin_bit_cast(unsigned, b); }
; DI float bflo(unsigned u) { return __uint_as_float(u << 16); }
; DI float bfhi(unsigned u) { return __uint_as_float(u & 0xffff0000u); }
;     DI void operator()(const f32x4 (&acc)[2][2][4][2], const Unit& u, int wr, int wc, int fr, int fq) const {
;     ...
;                     const int row = row0 + ai * HALF + m * 16; float ss = 0.f;
; #pragma unroll
;                     for (int bj = 0; bj < 2; ++bj) {
;                         const size_t off = (size_t)row * DM + col0 + bj * HALF; const u32x4 w = bw[ai][m][bj];
;                         const f32x4 b0 = (f32x4){bflo(w.x), bfhi(w.x), bflo(w.y), bfhi(w.y)}, b1 = (f32x4){bflo(w.z), bfhi(w.z), bflo(w.w), bfhi(w.w)};
;                         const f32x4 x0 = b0 + alpha * acc[ai][bj][m][0], x1 = b1 + alpha * acc[ai][bj][m][1];
;                         if (out) { *(f32x4*)(out + off) = x0; *(f32x4*)(out + off + 4) = x1; }
;                         if (xb) { u32x4 o; o.x = cvtpk(x0[0], x0[1]); o.y = cvtpk(x0[2], x0[3]); o.z = cvtpk(x1[0], x1[1]); o.w = cvtpk(x1[2], x1[3]); *(u32x4*)(xb + off) = o; }
;                         ss += (x0[0] * x0[0] + x0[1] * x0[1]) + (x0[2] * x0[2] + x0[3] * x0[3]) + (x1[0] * x1[0] + x1[1] * x1[1]) + (x1[2] * x1[2] + x1[3] * x1[3]);
.LBB0_533:
	s_nop 1
	s_waitcnt vmcnt(2)
	v_lshlrev_b32_e32 v150, 16, v138
	v_and_b32_e32 v151, 0xffff0000, v138
	v_lshlrev_b32_e32 v138, 16, v139
	v_and_b32_e32 v139, 0xffff0000, v139
	v_lshlrev_b32_e32 v158, 16, v140
	v_and_b32_e32 v159, 0xffff0000, v140
	v_lshlrev_b32_e32 v152, 16, v141
	v_and_b32_e32 v153, 0xffff0000, v141
	v_pk_fma_f32 v[140:141], s[84:85], v[24:25], v[138:139]
	v_pk_fma_f32 v[138:139], s[66:67], v[22:23], v[150:151]
	v_pk_fma_f32 v[152:153], s[84:85], v[20:21], v[152:153]
	s_and_b64 vcc, exec, s[8:9]
	v_pk_fma_f32 v[150:151], s[66:67], v[18:19], v[158:159]
	s_cbranch_vccnz .LBB0_535
	global_store_dwordx4 v[156:157], v[138:141], off offset:512
	global_store_dwordx4 v[156:157], v[150:153], off offset:528

; DI unsigned cvtpk(float lo, float hi) { f32x2_t v = {lo, hi}; bf16x2_t b = __builtin_convertvector(v, bf16x2_t); return __builtin_bit_cast(unsigned, b); }
; DI float bflo(unsigned u) { return __uint_as_float(u << 16); }
; DI float bfhi(unsigned u) { return __uint_as_float(u & 0xffff0000u); }
;     DI void operator()(const f32x4 (&acc)[2][2][4][2], const Unit& u, int wr, int wc, int fr, int fq) const {
;     ...
;                     const int row = row0 + ai * HALF + m * 16; float ss = 0.f;
; #pragma unroll
;                     for (int bj = 0; bj < 2; ++bj) {
;                         const size_t off = (size_t)row * DM + col0 + bj * HALF; const u32x4 w = bw[ai][m][bj];
;                         const f32x4 b0 = (f32x4){bflo(w.x), bfhi(w.x), bflo(w.y), bfhi(w.y)}, b1 = (f32x4){bflo(w.z), bfhi(w.z), bflo(w.w), bfhi(w.w)};
;                         const f32x4 x0 = b0 + alpha * acc[ai][bj][m][0], x1 = b1 + alpha * acc[ai][bj][m][1];
;                         if (out) { *(f32x4*)(out + off) = x0; *(f32x4*)(out + off + 4) = x1; }
;                         if (xb) { u32x4 o; o.x = cvtpk(x0[0], x0[1]); o.y = cvtpk(x0[2], x0[3]); o.z = cvtpk(x1[0], x1[1]); o.w = cvtpk(x1[2], x1[3]); *(u32x4*)(xb + off) = o; }
;                         ss += (x0[0] * x0[0] + x0[1] * x0[1]) + (x0[2] * x0[2] + x0[3] * x0[3]) + (x1[0] * x1[0] + x1[1] * x1[1]) + (x1[2] * x1[2] + x1[3] * x1[3]);
.LBB0_541:
	s_waitcnt lgkmcnt(0)
	v_lshlrev_b64 v[138:139], 10, v[218:219]
	v_lshl_add_u64 v[142:143], v[138:139], 0, v[220:221]
	s_waitcnt vmcnt(1)
	v_lshlrev_b32_e32 v138, 16, v134
	v_and_b32_e32 v139, 0xffff0000, v134
	v_lshlrev_b32_e32 v134, 16, v135
	v_and_b32_e32 v135, 0xffff0000, v135
	v_lshlrev_b32_e32 v144, 16, v136
	v_and_b32_e32 v145, 0xffff0000, v136
	v_lshlrev_b32_e32 v140, 16, v137
	v_and_b32_e32 v141, 0xffff0000, v137
	v_pk_fma_f32 v[136:137], s[84:85], v[16:17], v[134:135]
	v_pk_fma_f32 v[134:135], s[66:67], v[14:15], v[138:139]
	v_pk_fma_f32 v[140:141], s[84:85], v[12:13], v[140:141]
	v_pk_fma_f32 v[138:139], s[66:67], v[10:11], v[144:145]
	s_and_b64 vcc, exec, s[8:9]
	v_lshl_add_u64 v[148:149], v[142:143], 2, s[40:41]
	s_cbranch_vccnz .LBB0_543
	global_store_dwordx4 v[148:149], v[134:137], off
	global_store_dwordx4 v[148:149], v[138:141], off offset:16

; DI unsigned cvtpk(float lo, float hi) { f32x2_t v = {lo, hi}; bf16x2_t b = __builtin_convertvector(v, bf16x2_t); return __builtin_bit_cast(unsigned, b); }
; DI float bflo(unsigned u) { return __uint_as_float(u << 16); }
; DI float bfhi(unsigned u) { return __uint_as_float(u & 0xffff0000u); }
;     DI void operator()(const f32x4 (&acc)[2][2][4][2], const Unit& u, int wr, int wc, int fr, int fq) const {
;     ...
;                     const int row = row0 + ai * HALF + m * 16; float ss = 0.f;
; #pragma unroll
;                     for (int bj = 0; bj < 2; ++bj) {
;                         const size_t off = (size_t)row * DM + col0 + bj * HALF; const u32x4 w = bw[ai][m][bj];
;                         const f32x4 b0 = (f32x4){bflo(w.x), bfhi(w.x), bflo(w.y), bfhi(w.y)}, b1 = (f32x4){bflo(w.z), bfhi(w.z), bflo(w.w), bfhi(w.w)};
;                         const f32x4 x0 = b0 + alpha * acc[ai][bj][m][0], x1 = b1 + alpha * acc[ai][bj][m][1];
;                         if (out) { *(f32x4*)(out + off) = x0; *(f32x4*)(out + off + 4) = x1; }
;                         if (xb) { u32x4 o; o.x = cvtpk(x0[0], x0[1]); o.y = cvtpk(x0[2], x0[3]); o.z = cvtpk(x1[0], x1[1]); o.w = cvtpk(x1[2], x1[3]); *(u32x4*)(xb + off) = o; }
;                         ss += (x0[0] * x0[0] + x0[1] * x0[1]) + (x0[2] * x0[2] + x0[3] * x0[3]) + (x1[0] * x1[0] + x1[1] * x1[1]) + (x1[2] * x1[2] + x1[3] * x1[3]);
.LBB0_545:
	s_nop 1
	s_waitcnt vmcnt(0)
	v_lshlrev_b32_e32 v142, 16, v130
	v_and_b32_e32 v143, 0xffff0000, v130
	v_lshlrev_b32_e32 v130, 16, v131
	v_and_b32_e32 v131, 0xffff0000, v131
	v_lshlrev_b32_e32 v150, 16, v132
	v_and_b32_e32 v151, 0xffff0000, v132
	v_lshlrev_b32_e32 v144, 16, v133
	v_and_b32_e32 v145, 0xffff0000, v133
	v_pk_fma_f32 v[132:133], s[84:85], v[8:9], v[130:131]
	v_pk_fma_f32 v[130:131], s[66:67], v[6:7], v[142:143]
	v_pk_fma_f32 v[144:145], s[84:85], v[4:5], v[144:145]
	s_and_b64 vcc, exec, s[8:9]
	v_pk_fma_f32 v[142:143], s[66:67], v[2:3], v[150:151]
	s_cbranch_vccnz .LBB0_547
	global_store_dwordx4 v[148:149], v[130:133], off offset:512
	global_store_dwordx4 v[148:149], v[142:145], off offset:528
